# attention: P fragments fed to PV in accumulator order (no permlane swaps, V image key order matched), 7-deep V reads, K reads one pair deeper, row-sum/max chain trimmed, decision chain behind PV; P0a
# speedup vs baseline: 1.0121x; 1.0121x over previous
; #define WAIT_BAR() asm volatile("s_waitcnt vmcnt(0) lgkmcnt(0)\n\ts_barrier" ::: "memory")
;     ...
;   { const int kkl = (lane >> 2) & 7, cl = 32 * (lane >> 5) + (lane & 3) * 8;
;     const int kk0 = 8 * (wid >> 1) + kkl, kk1 = 8 * ((wid + 8) >> 1) + kkl;
;     const int key0 = (kk0 & ~0xC) | ((kk0 & 4) << 1) | ((kk0 & 8) >> 1), key1 = (kk1 & ~0xC) | ((kk1 & 4) << 1) | ((kk1 & 8) >> 1);
;     vo0 = (unsigned)(key0 * LD + 64 * (wid & 1) + cl) * 2u; vo1 = (unsigned)(key1 * LD + 64 * (wid & 1) + cl) * 2u; }
;     ...
;     DMA(0, 0); DMA(1, 1); WAIT_BAR();
;     { qkt(pA0, pA1, K_lds, qr, r32, hi); rowdecide(rowmax16(pA0), pA0, pA1, negm, alA);
.LBB0_693:
	s_ashr_i32 s1, s4, 4
	s_and_b32 s5, s1, 0x3ffff0
	v_and_b32_e32 v169, 63, v1
	v_bfe_u32 v3, v1, 2, 2
	v_and_b32_e32 v4, 32, v1
	v_lshlrev_b32_e32 v5, 3, v1
	s_add_i32 s19, s18, 8
	v_lshrrev_b32_e32 v1, 2, v1
	s_and_b32 s1, s1, 8
	s_lshl_b32 s24, s19, 2
	v_and_b32_e32 v1, 4, v1
	s_or_b32 s1, s5, s1
	s_lshl_b32 s5, s19, 2
	v_and_or_b32 v4, v5, 24, v4
	v_or3_b32 v5, s1, v3, v1
	s_and_b32 s1, s24, 0x3ffff0
	s_and_b32 s5, s5, 8
	s_or_b32 s1, s1, s5
	v_or3_b32 v1, s1, v3, v1
	s_and_b32 s1, s4, 64
	s_mul_i32 s42, s0, 0x1080000
	v_lshlrev_b32_e32 v3, 10, v5
	v_lshlrev_b32_e32 v1, 10, v1
	s_mul_hi_i32 s5, s0, 0x1080000
	s_add_u32 s0, s40, s42
	v_or3_b32 v3, v3, s1, v4
	v_or3_b32 v1, v1, s1, v4
	s_addc_u32 s1, s41, s5
	s_add_u32 s24, s62, s42
	s_addc_u32 s25, s63, s5
	s_add_u32 s52, s24, s6
	s_addc_u32 s53, s25, 0
	s_add_u32 s64, s0, s6
	s_addc_u32 s65, s1, 0
	s_lshl_b32 s24, s18, 10
	s_cmp_lg_u32 0, -1
	v_lshlrev_b32_e32 v2, 11, v169
	s_cselect_b32 s0, 0, 0
	v_lshl_add_u32 v166, s18, 4, v2
	v_lshlrev_b32_e32 v170, 1, v1
	v_lshlrev_b32_e32 v1, 1, v3
	s_add_i32 s1, s24, s0
	v_lshl_add_u64 v[32:33], s[64:65], 0, v[166:167]
	s_add_i32 s25, s1, 0xc000
	s_mov_b32 s34, m0
	s_mov_b32 m0, s25
	s_nop 0
	global_load_lds_dwordx4 v[32:33], off
	s_mov_b32 m0, s34
	v_mov_b32_e32 v166, v1
	v_lshl_add_u64 v[2:3], s[52:53], 0, v[166:167]
	s_mov_b32 s25, m0
	s_mov_b32 m0, s1
	s_nop 0
	global_load_lds_dwordx4 v[2:3], off
	s_mov_b32 m0, s25
	s_lshl_b32 s25, s19, 10
	v_mov_b32_e32 v171, v167
	s_add_i32 s19, s25, s0
	v_lshl_add_u64 v[2:3], s[52:53], 0, v[170:171]
	s_mov_b32 s34, m0
	s_mov_b32 m0, s19
	s_nop 0
	global_load_lds_dwordx4 v[2:3], off
	s_mov_b32 m0, s34
	s_add_u32 s54, s52, 0x20000
	s_addc_u32 s55, s53, 0
	v_lshl_add_u64 v[2:3], v[32:33], 0, s[8:9]
	s_add_i32 s1, s1, 0xe000
	s_mov_b32 s19, m0
	s_mov_b32 m0, s1
	s_nop 0
	global_load_lds_dwordx4 v[2:3], off
	s_mov_b32 m0, s19
	s_addk_i32 s0, 0x4000
	v_lshl_add_u64 v[2:3], s[54:55], 0, v[166:167]
	s_add_i32 s1, s24, s0
	s_mov_b32 s19, m0
	s_mov_b32 m0, s1
	s_nop 0
	global_load_lds_dwordx4 v[2:3], off
	s_mov_b32 m0, s19
	v_lshl_add_u64 v[2:3], s[54:55], 0, v[170:171]
	s_add_i32 s0, s25, s0
	s_mov_b32 s1, m0
	s_mov_b32 m0, s0
	s_nop 0
	global_load_lds_dwordx4 v[2:3], off
	s_mov_b32 m0, s1
	v_lshlrev_b32_e32 v180, 10, v0
	v_lshlrev_b32_e32 v181, 4, v34
	s_waitcnt vmcnt(0) lgkmcnt(0)
	s_barrier
	v_add3_u32 v35, 0, v180, v181
	ds_read_b128 v[0:3], v35 offset:49152
	ds_read_b128 v[4:7], v35 offset:49664
	s_waitcnt vmcnt(3) lgkmcnt(1)
	v_mfma_f32_32x32x16_bf16 v[16:31], v[0:3], v[156:159], 0
	ds_read_b128 v[36:39], v35 offset:51200
	ds_read_b128 v[40:43], v35 offset:51712
	v_mov_b32_e32 v182, 1.0
	s_waitcnt lgkmcnt(2)
	v_mfma_f32_32x32x16_bf16 v[0:15], v[4:7], v[156:159], 0
	s_waitcnt vmcnt(2) lgkmcnt(0)
	v_mfma_f32_32x32x16_bf16 v[0:15], v[40:43], v[152:155], v[0:15]
	v_mfma_f32_32x32x16_bf16 v[16:31], v[36:39], v[152:155], v[16:31]
	ds_read_b128 v[36:39], v35 offset:53248
	ds_read_b128 v[40:43], v35 offset:53760
	s_waitcnt vmcnt(1) lgkmcnt(0)
	v_mfma_f32_32x32x16_bf16 v[0:15], v[40:43], v[148:151], v[0:15]
	v_mfma_f32_32x32x16_bf16 v[16:31], v[36:39], v[148:151], v[16:31]
	ds_read_b128 v[36:39], v35 offset:55296
	ds_read_b128 v[40:43], v35 offset:55808
	s_waitcnt vmcnt(0) lgkmcnt(0)
	v_mfma_f32_32x32x16_bf16 v[0:15], v[40:43], v[144:147], v[0:15]
	v_mfma_f32_32x32x16_bf16 v[16:31], v[36:39], v[144:147], v[16:31]
	s_nop 10
	v_max_f32_e32 v37, v1, v1
	v_max_f32_e32 v38, v0, v0
	v_max_f32_e32 v37, v38, v37
	v_max3_f32 v38, v3, v4, v5
	v_max3_f32 v37, v37, v2, v6
	v_max3_f32 v38, v38, v8, v9
	v_max3_f32 v37, v37, v7, v10
	v_max3_f32 v35, v16, v17, v18
	v_max3_f32 v36, v19, v20, v21
	v_max3_f32 v35, v35, v22, v23
	v_max3_f32 v36, v36, v24, v25
	v_max3_f32 v35, v35, v26, v27
	v_max3_f32 v38, v38, v12, v13
	v_max3_f32 v37, v37, v11, v14
	v_max3_f32 v36, v36, v28, v29
	v_max3_f32 v35, v35, v30, v31
	v_max3_f32 v37, v37, v15, v38
	v_max3_f32 v35, v35, v36, v37
	v_mov_b32_e32 v36, v35
	s_nop 1
	v_permlane32_swap_b32_e32 v35, v36
	v_max_f32_e32 v36, v36, v36
	v_max_f32_e32 v35, v35, v35
	v_max_f32_e32 v35, v35, v36
	v_cmp_lt_f32_e32 vcc, s47, v35
	s_cbranch_vccnz .LBB0_741

;     ...
;     f32x16 pA0, pA1, pB0, pB1; float alA, alB; bf16x8 pa0, pa1, pa2, pa3;
;     int sp = 0, sc_ = 1, sn = 2;
.LBB0_695:
	s_lshl_b32 s43, s34, 13
	s_mov_b32 s42, s38
	v_lshl_add_u32 v185, s42, 13, v184
	ds_read_b128 v[112:115], v185 offset:49152
	ds_read_b128 v[186:189], v185 offset:49664
	ds_read_b128 v[190:193], v185 offset:51200
	ds_read_b128 v[194:197], v185 offset:51712
	s_add_i32 s38, s43, s39
	s_mov_b32 m0, s38
	v_lshl_add_u64 v[212:213], s[68:69], 0, v[166:167]
	global_load_lds_dwordx4 v[172:173], off
	s_lshl_b32 s38, s34, 14
	s_add_i32 s45, s38, s24
	s_mov_b32 m0, s45
	v_lshl_add_u64 v[214:215], s[68:69], 0, v[170:171]
	global_load_lds_dwordx4 v[212:213], off
	s_add_i32 s38, s38, s25
	s_mov_b32 m0, s38
	s_mov_b32 s38, s44
	global_load_lds_dwordx4 v[214:215], off
	s_waitcnt lgkmcnt(3)
	v_mfma_f32_32x32x16_bf16 v[128:143], v[112:115], v[156:159], v[64:79]
	ds_read_b128 v[224:227], v185 offset:53248
	ds_read_b128 v[198:201], v185 offset:53760
	v_add_f32_e32 v116, v98, v96
	v_add_f32_e32 v117, v99, v97
	v_cvt_pk_bf16_f32 v96, v96, v97
	v_cvt_pk_bf16_f32 v97, v98, v99
	v_cvt_pk_bf16_f32 v98, v100, v101
	v_cvt_pk_bf16_f32 v99, v102, v103
	v_add_f32_e32 v100, v100, v116
	v_add_f32_e32 v101, v101, v117
	s_waitcnt lgkmcnt(4)
	v_mfma_f32_32x32x16_bf16 v[112:127], v[186:189], v[156:159], v[64:79]
	v_add_f32_e32 v100, v102, v100
	v_add_f32_e32 v101, v103, v101
	s_waitcnt lgkmcnt(3)
	v_mfma_f32_32x32x16_bf16 v[128:143], v[190:193], v[152:155], v[128:143]
	ds_read_b128 v[228:231], v185 offset:55296
	ds_read_b128 v[232:235], v185 offset:55808
	v_add_f32_e32 v100, v104, v100
	v_add_f32_e32 v101, v105, v101
	v_add_f32_e32 v202, v106, v100
	v_add_f32_e32 v203, v107, v101
	v_cvt_pk_bf16_f32 v100, v104, v105
	v_cvt_pk_bf16_f32 v101, v106, v107
	v_cvt_pk_bf16_f32 v102, v108, v109
	v_cvt_pk_bf16_f32 v103, v110, v111
	s_waitcnt lgkmcnt(4)
	v_mfma_f32_32x32x16_bf16 v[112:127], v[194:197], v[152:155], v[112:127]
	v_add_f32_e32 v104, v108, v202
	v_add_f32_e32 v105, v109, v203
	v_add_f32_e32 v190, v110, v104
	v_add_f32_e32 v191, v111, v105
	s_waitcnt lgkmcnt(3)
	v_mfma_f32_32x32x16_bf16 v[128:143], v[224:227], v[148:151], v[128:143]
	v_add_f32_e32 v185, v80, v190
	v_add_f32_e32 v190, v81, v191
	v_add_f32_e32 v185, v82, v185
	v_add_f32_e32 v190, v83, v190
	v_cvt_pk_bf16_f32 v80, v80, v81
	v_cvt_pk_bf16_f32 v81, v82, v83
	v_cvt_pk_bf16_f32 v82, v84, v85
	v_cvt_pk_bf16_f32 v83, v86, v87
	s_waitcnt lgkmcnt(2)
	v_mfma_f32_32x32x16_bf16 v[112:127], v[198:201], v[148:151], v[112:127]
	s_lshl_b32 s44, s38, 14
	v_add_u32_e32 v189, s44, v183
	ds_read_b64_tr_b16 v[194:195], v189 offset:0
	ds_read_b64_tr_b16 v[196:197], v189 offset:0x800
	ds_read_b64_tr_b16 v[198:199], v189 offset:0x1000
	ds_read_b64_tr_b16 v[200:201], v189 offset:0x1800
	ds_read_b64_tr_b16 v[212:213], v189 offset:0x2000
	ds_read_b64_tr_b16 v[214:215], v189 offset:0x2800
	v_add_f32_e32 v84, v84, v185
	v_add_f32_e32 v85, v85, v190
	v_add_f32_e32 v84, v86, v84
	v_add_f32_e32 v85, v87, v85
	s_waitcnt lgkmcnt(7)
	v_mfma_f32_32x32x16_bf16 v[128:143], v[228:231], v[144:147], v[128:143]
	ds_read_b64_tr_b16 v[190:191], v189 offset:0x3000
	ds_read_b64_tr_b16 v[192:193], v189 offset:0x3800
	ds_read_b64_tr_b16 v[216:217], v189 offset:0x200
	ds_read_b64_tr_b16 v[218:219], v189 offset:0xa00
	v_add_f32_e32 v84, v88, v84
	v_add_f32_e32 v85, v89, v85
	v_add_f32_e32 v185, v90, v84
	v_add_f32_e32 v186, v91, v85
	v_cvt_pk_bf16_f32 v84, v88, v89
	v_cvt_pk_bf16_f32 v85, v90, v91
	v_cvt_pk_bf16_f32 v86, v92, v93
	v_cvt_pk_bf16_f32 v87, v94, v95
	s_waitcnt lgkmcnt(10)
	v_mfma_f32_32x32x16_bf16 v[112:127], v[232:235], v[144:147], v[112:127]
	v_add_f32_e32 v88, v92, v185
	v_add_f32_e32 v89, v93, v186
	v_add_f32_e32 v88, v94, v88
	v_add_f32_e32 v89, v95, v89
	ds_read_b64_tr_b16 v[220:221], v189 offset:0x1200
	ds_read_b64_tr_b16 v[222:223], v189 offset:0x1a00
	ds_read_b64_tr_b16 v[224:225], v189 offset:0x2200
	ds_read_b64_tr_b16 v[226:227], v189 offset:0x2a00
	s_waitcnt lgkmcnt(12)
	v_mfma_f32_32x32x16_bf16 v[48:63], v[96:99], v[194:197], v[48:63]
	v_max_f32_e32 v90, v128, v129
	v_max3_f32 v91, v131, v132, v133
	v_max3_f32 v90, v90, v130, v134
	v_max3_f32 v91, v91, v136, v137
	ds_read_b64_tr_b16 v[194:195], v189 offset:0x3200
	ds_read_b64_tr_b16 v[196:197], v189 offset:0x3a00
	s_waitcnt lgkmcnt(12)
	v_mfma_f32_32x32x16_bf16 v[48:63], v[100:103], v[198:201], v[48:63]
	v_max3_f32 v90, v90, v135, v138
	v_max3_f32 v91, v91, v140, v141
	v_max3_f32 v90, v90, v139, v142
	v_max3_f32 v90, v90, v143, v91
	v_add_f32_e32 v186, v88, v89
	v_mov_b32_e32 v187, v186
	ds_read_b64_tr_b16 v[198:199], v189 offset:0x400
	ds_read_b64_tr_b16 v[200:201], v189 offset:0xc00
	s_waitcnt lgkmcnt(12)
	v_mfma_f32_32x32x16_bf16 v[48:63], v[80:83], v[212:215], v[48:63]
	v_max3_f32 v88, v112, v113, v114
	v_max3_f32 v89, v115, v116, v117
	v_max3_f32 v88, v88, v118, v119
	v_max3_f32 v89, v89, v120, v121
	v_permlane32_swap_b32_e32 v186, v187
	v_max3_f32 v88, v88, v122, v123
	ds_read_b64_tr_b16 v[212:213], v189 offset:0x1400
	ds_read_b64_tr_b16 v[214:215], v189 offset:0x1c00
	s_waitcnt lgkmcnt(12)
	v_mfma_f32_32x32x16_bf16 v[48:63], v[84:87], v[190:193], v[48:63]
	v_max3_f32 v89, v89, v124, v125
	v_max3_f32 v88, v88, v126, v127
	v_max3_f32 v88, v90, v88, v89
	v_mov_b32_e32 v89, v88
	ds_read_b64_tr_b16 v[190:191], v189 offset:0x2400
	ds_read_b64_tr_b16 v[192:193], v189 offset:0x2c00
	s_waitcnt lgkmcnt(12)
	v_mfma_f32_32x32x16_bf16 v[32:47], v[96:99], v[216:219], v[32:47]
	v_permlane32_swap_b32_e32 v88, v89
	v_max_f32_e32 v88, v88, v89
	v_cmp_lt_f32_e32 vcc, s47, v88
	v_mov_b32_e32 v188, 1.0
	s_cbranch_vccnz .LBB0_707

;     ...
;     f32x16 pA0, pA1, pB0, pB1; float alA, alB; bf16x8 pa0, pa1, pa2, pa3;
;     int sp = 0, sc_ = 1, sn = 2;
.LBB0_700:
	s_add_u32 s48, s68, 0x20000
	s_addc_u32 s49, s69, 0
	s_lshl_b32 s45, s38, 13
	s_add_i32 s45, s45, s39
	s_waitcnt vmcnt(0) lgkmcnt(0)
	s_barrier
	v_add_u32_e32 v185, s43, v184
	ds_read_b128 v[80:83], v185 offset:49152
	ds_read_b128 v[190:193], v185 offset:49664
	ds_read_b128 v[194:197], v185 offset:51200
	ds_read_b128 v[198:201], v185 offset:51712
	s_mov_b32 m0, s45
	v_lshl_add_u64 v[212:213], v[172:173], 0, s[8:9]
	global_load_lds_dwordx4 v[212:213], off
	s_add_i32 s45, s44, s24
	s_mov_b32 m0, s45
	v_lshl_add_u64 v[214:215], s[48:49], 0, v[166:167]
	global_load_lds_dwordx4 v[214:215], off
	s_add_i32 s44, s44, s25
	s_mov_b32 m0, s44
	v_lshl_add_u64 v[212:213], s[48:49], 0, v[170:171]
	global_load_lds_dwordx4 v[212:213], off
	s_waitcnt lgkmcnt(3)
	v_mfma_f32_32x32x16_bf16 v[96:111], v[80:83], v[156:159], v[64:79]
	ds_read_b128 v[224:227], v185 offset:53248
	ds_read_b128 v[202:205], v185 offset:53760
	v_add_f32_e32 v84, v130, v128
	v_add_f32_e32 v85, v131, v129
	v_cvt_pk_bf16_f32 v128, v128, v129
	v_cvt_pk_bf16_f32 v129, v130, v131
	v_cvt_pk_bf16_f32 v130, v132, v133
	v_cvt_pk_bf16_f32 v131, v134, v135
	v_add_f32_e32 v80, v132, v84
	v_add_f32_e32 v81, v133, v85
	v_add_f32_e32 v132, v134, v80
	v_add_f32_e32 v133, v135, v81
	s_waitcnt lgkmcnt(4)
	v_mfma_f32_32x32x16_bf16 v[80:95], v[190:193], v[156:159], v[64:79]
	s_waitcnt lgkmcnt(3)
	v_mfma_f32_32x32x16_bf16 v[96:111], v[194:197], v[152:155], v[96:111]
	ds_read_b128 v[228:231], v185 offset:55296
	ds_read_b128 v[232:235], v185 offset:55808
	v_add_f32_e32 v132, v136, v132
	v_add_f32_e32 v133, v137, v133
	v_add_f32_e32 v189, v138, v132
	v_add_f32_e32 v206, v139, v133
	v_cvt_pk_bf16_f32 v132, v136, v137
	v_cvt_pk_bf16_f32 v133, v138, v139
	v_cvt_pk_bf16_f32 v134, v140, v141
	v_cvt_pk_bf16_f32 v135, v142, v143
	s_waitcnt lgkmcnt(4)
	v_mfma_f32_32x32x16_bf16 v[80:95], v[198:201], v[152:155], v[80:95]
	v_add_f32_e32 v136, v140, v189
	v_add_f32_e32 v137, v141, v206
	v_add_f32_e32 v189, v142, v136
	v_add_f32_e32 v194, v143, v137
	s_waitcnt lgkmcnt(3)
	v_mfma_f32_32x32x16_bf16 v[96:111], v[224:227], v[148:151], v[96:111]
	v_add_f32_e32 v185, v112, v189
	v_add_f32_e32 v189, v113, v194
	v_add_f32_e32 v185, v114, v185
	v_add_f32_e32 v189, v115, v189
	v_cvt_pk_bf16_f32 v112, v112, v113
	v_cvt_pk_bf16_f32 v113, v114, v115
	v_cvt_pk_bf16_f32 v114, v116, v117
	v_cvt_pk_bf16_f32 v115, v118, v119
	s_waitcnt lgkmcnt(2)
	v_mfma_f32_32x32x16_bf16 v[80:95], v[202:205], v[148:151], v[80:95]
	v_lshl_add_u32 v206, s42, 14, v183
	ds_read_b64_tr_b16 v[198:199], v206 offset:0
	ds_read_b64_tr_b16 v[200:201], v206 offset:0x800
	ds_read_b64_tr_b16 v[190:191], v206 offset:0x1000
	ds_read_b64_tr_b16 v[192:193], v206 offset:0x1800
	ds_read_b64_tr_b16 v[202:203], v206 offset:0x2000
	ds_read_b64_tr_b16 v[204:205], v206 offset:0x2800
	v_add_f32_e32 v116, v116, v185
	v_add_f32_e32 v117, v117, v189
	v_add_f32_e32 v116, v118, v116
	v_add_f32_e32 v117, v119, v117
	s_waitcnt lgkmcnt(7)
	v_mfma_f32_32x32x16_bf16 v[96:111], v[228:231], v[144:147], v[96:111]
	ds_read_b64_tr_b16 v[212:213], v206 offset:0x3000
	ds_read_b64_tr_b16 v[214:215], v206 offset:0x3800
	ds_read_b64_tr_b16 v[216:217], v206 offset:0x200
	ds_read_b64_tr_b16 v[218:219], v206 offset:0xa00
	v_add_f32_e32 v116, v120, v116
	v_add_f32_e32 v117, v121, v117
	v_add_f32_e32 v185, v122, v116
	v_add_f32_e32 v189, v123, v117
	v_cvt_pk_bf16_f32 v116, v120, v121
	v_cvt_pk_bf16_f32 v117, v122, v123
	v_cvt_pk_bf16_f32 v118, v124, v125
	v_cvt_pk_bf16_f32 v119, v126, v127
	s_waitcnt lgkmcnt(10)
	v_mfma_f32_32x32x16_bf16 v[80:95], v[232:235], v[144:147], v[80:95]
	v_add_f32_e32 v120, v124, v185
	v_add_f32_e32 v121, v125, v189
	v_add_f32_e32 v120, v126, v120
	v_add_f32_e32 v121, v127, v121
	ds_read_b64_tr_b16 v[220:221], v206 offset:0x1200
	ds_read_b64_tr_b16 v[222:223], v206 offset:0x1a00
	ds_read_b64_tr_b16 v[224:225], v206 offset:0x2200
	ds_read_b64_tr_b16 v[226:227], v206 offset:0x2a00
	s_waitcnt lgkmcnt(12)
	v_mfma_f32_32x32x16_bf16 v[48:63], v[128:131], v[198:201], v[48:63]
	v_max_f32_e32 v122, v96, v97
	v_max3_f32 v123, v99, v100, v101
	v_max3_f32 v122, v122, v98, v102
	v_max3_f32 v123, v123, v104, v105
	ds_read_b64_tr_b16 v[198:199], v206 offset:0x3200
	ds_read_b64_tr_b16 v[200:201], v206 offset:0x3a00
	s_waitcnt lgkmcnt(12)
	v_mfma_f32_32x32x16_bf16 v[48:63], v[132:135], v[190:193], v[48:63]
	v_max3_f32 v122, v122, v103, v106
	v_max3_f32 v123, v123, v108, v109
	v_max3_f32 v122, v122, v107, v110
	v_max3_f32 v122, v122, v111, v123
	v_add_f32_e32 v120, v120, v121
	v_mov_b32_e32 v121, v120
	ds_read_b64_tr_b16 v[190:191], v206 offset:0x400
	ds_read_b64_tr_b16 v[192:193], v206 offset:0xc00
	s_waitcnt lgkmcnt(12)
	v_mfma_f32_32x32x16_bf16 v[48:63], v[112:115], v[202:205], v[48:63]
	v_max3_f32 v123, v80, v81, v82
	v_max3_f32 v124, v83, v84, v85
	v_max3_f32 v123, v123, v86, v87
	v_max3_f32 v124, v124, v88, v89
	v_permlane32_swap_b32_e32 v120, v121
	v_max3_f32 v123, v123, v90, v91
	ds_read_b64_tr_b16 v[202:203], v206 offset:0x1400
	ds_read_b64_tr_b16 v[204:205], v206 offset:0x1c00
	s_waitcnt lgkmcnt(12)
	v_mfma_f32_32x32x16_bf16 v[48:63], v[116:119], v[212:215], v[48:63]
	v_max3_f32 v124, v124, v92, v93
	v_max3_f32 v123, v123, v94, v95
	v_max3_f32 v122, v122, v123, v124
	v_mov_b32_e32 v123, v122
	ds_read_b64_tr_b16 v[212:213], v206 offset:0x2400
	ds_read_b64_tr_b16 v[214:215], v206 offset:0x2c00
	s_waitcnt lgkmcnt(12)
	v_mfma_f32_32x32x16_bf16 v[32:47], v[128:131], v[216:219], v[32:47]
	v_permlane32_swap_b32_e32 v122, v123
	v_max_f32_e32 v122, v122, v123
	v_cmp_lt_f32_e32 vcc, s47, v122
	v_mov_b32_e32 v185, 1.0
	s_cbranch_vccnz .LBB0_708

.LBB0_709:
	v_add3_u32 v166, s72, v181, v180
	ds_read_b128 v[112:115], v166
	ds_read_b128 v[170:173], v166 offset:512
	s_waitcnt lgkmcnt(1)
	v_mfma_f32_32x32x16_bf16 v[128:143], v[112:115], v[156:159], v[64:79]
	ds_read_b128 v[180:183], v166 offset:2048
	ds_read_b128 v[186:189], v166 offset:2560
	v_add_f32_e32 v116, 0, v96
	v_add_f32_e32 v117, 0, v97
	v_add_f32_e32 v116, v98, v116
	v_add_f32_e32 v117, v99, v117
	v_cvt_pk_bf16_f32 v96, v96, v97
	v_cvt_pk_bf16_f32 v97, v98, v99
	v_cvt_pk_bf16_f32 v98, v100, v101
	v_cvt_pk_bf16_f32 v99, v102, v103
	s_nop 0
	v_add_f32_e32 v100, v100, v116
	v_add_f32_e32 v101, v101, v117
	s_waitcnt lgkmcnt(2)
	v_mfma_f32_32x32x16_bf16 v[112:127], v[170:173], v[156:159], v[64:79]
	v_add_f32_e32 v100, v102, v100
	v_add_f32_e32 v101, v103, v101
	s_waitcnt lgkmcnt(1)
	v_mfma_f32_32x32x16_bf16 v[128:143], v[180:183], v[152:155], v[128:143]
	ds_read_b128 v[156:159], v166 offset:4096
	ds_read_b128 v[170:173], v166 offset:4608
	v_add_f32_e32 v100, v104, v100
	v_add_f32_e32 v101, v105, v101
	v_add_f32_e32 v184, v106, v100
	v_add_f32_e32 v190, v107, v101
	v_cvt_pk_bf16_f32 v100, v104, v105
	v_cvt_pk_bf16_f32 v101, v106, v107
	v_cvt_pk_bf16_f32 v102, v108, v109
	v_cvt_pk_bf16_f32 v103, v110, v111
	s_waitcnt lgkmcnt(2)
	v_mfma_f32_32x32x16_bf16 v[112:127], v[186:189], v[152:155], v[112:127]
	v_add_f32_e32 v104, v108, v184
	v_add_f32_e32 v105, v109, v190
	v_add_f32_e32 v180, v110, v104
	v_add_f32_e32 v181, v111, v105
	s_waitcnt lgkmcnt(1)
	v_mfma_f32_32x32x16_bf16 v[128:143], v[156:159], v[148:151], v[128:143]
	ds_read_b128 v[104:107], v166 offset:6144
	ds_read_b128 v[108:111], v166 offset:6656
	v_add_f32_e32 v152, v80, v180
	v_add_f32_e32 v153, v81, v181
	v_add_f32_e32 v152, v82, v152
	v_add_f32_e32 v153, v83, v153
	v_cvt_pk_bf16_f32 v80, v80, v81
	v_cvt_pk_bf16_f32 v81, v82, v83
	v_cvt_pk_bf16_f32 v82, v84, v85
	v_cvt_pk_bf16_f32 v83, v86, v87
	s_waitcnt lgkmcnt(2)
	v_mfma_f32_32x32x16_bf16 v[112:127], v[170:173], v[148:151], v[112:127]
	v_add_f32_e32 v84, v84, v152
	v_add_f32_e32 v85, v85, v153
	v_add_f32_e32 v84, v86, v84
	v_add_f32_e32 v85, v87, v85
	s_waitcnt lgkmcnt(1)
	v_mfma_f32_32x32x16_bf16 v[128:143], v[104:107], v[144:147], v[128:143]
	v_add_f32_e32 v84, v88, v84
	v_add_f32_e32 v85, v89, v85
	v_add_f32_e32 v148, v90, v84
	v_add_f32_e32 v149, v91, v85
	v_cvt_pk_bf16_f32 v84, v88, v89
	v_cvt_pk_bf16_f32 v85, v90, v91
	v_cvt_pk_bf16_f32 v86, v92, v93
	v_cvt_pk_bf16_f32 v87, v94, v95
	s_waitcnt lgkmcnt(0)
	v_mfma_f32_32x32x16_bf16 v[112:127], v[108:111], v[144:147], v[112:127]
	s_nop 1
	v_max_f32_e32 v90, v129, v129
	v_max_f32_e32 v91, v128, v128
	v_max_f32_e32 v90, v91, v90
	v_max3_f32 v91, v131, v132, v133
	v_max3_f32 v90, v90, v130, v134
	v_max3_f32 v91, v91, v136, v137
	v_max3_f32 v90, v90, v135, v138
	v_add_f32_e32 v88, v92, v148
	v_add_f32_e32 v89, v93, v149
	v_max3_f32 v91, v91, v140, v141
	v_max3_f32 v90, v90, v139, v142
	v_add_f32_e32 v88, v94, v88
	v_add_f32_e32 v89, v95, v89
	v_max3_f32 v90, v90, v143, v91
	s_nop 0
	v_add_f32_e32 v88, v88, v89
	v_mov_b32_e32 v89, v88
	s_nop 1
	v_permlane32_swap_b32_e32 v88, v89
	v_max3_f32 v91, v112, v113, v114
	v_max3_f32 v92, v115, v116, v117
	v_max3_f32 v91, v91, v118, v119
	v_max3_f32 v92, v92, v120, v121
	v_max3_f32 v91, v91, v122, v123
	v_max3_f32 v92, v92, v124, v125
	v_max3_f32 v91, v91, v126, v127
	v_max3_f32 v90, v90, v91, v92
	v_mov_b32_e32 v91, v90
	s_nop 1
	v_permlane32_swap_b32_e32 v90, v91
	v_max_f32_e32 v91, v91, v91
	v_max_f32_e32 v90, v90, v90
	v_max_f32_e32 v91, v90, v91
	v_cmp_lt_f32_e32 vcc, s47, v91
	v_mov_b32_e32 v90, 1.0
	s_cbranch_vccnz .LBB0_742

; __device__ __forceinline__ unsigned cvt_pk_bf16(float lo, float hi) { f32x2 v = {lo, hi}; bf16x2_t b = __builtin_convertvector(v, bf16x2_t); return __builtin_bit_cast(unsigned, b); }
; #define SBAR() __builtin_amdgcn_sched_barrier(0)
; __device__ __forceinline__ int crow(int r, int hi) { return (r & 3) + 8 * (r >> 2) + 4 * hi; }
; #define FINA(I, P0, P1) finA<I>(P0, P1, ps0, ps1, cv_, pa0, pa1, pa2, pa3)
;     ...
;     { float ps0 = 0.f, ps1 = 0.f; unsigned cv_[4];
;       FINA(0, pB0, pB1); FINA(1, pB0, pB1); FINA(2, pB0, pB1); FINA(3, pB0, pB1); FINA(4, pB0, pB1); FINA(5, pB0, pB1); FINA(6, pB0, pB1); FINA(7, pB0, pB1);
;       float ps = ps0 + ps1; auto rr = __builtin_amdgcn_permlane32_swap(__float_as_uint(ps), __float_as_uint(ps), false, false);
;       ps = __uint_as_float(rr[0]) + __uint_as_float(rr[1]); l_reg = l_reg * alB + ps; }
;     SBAR();
;     pv_d0(o, vb0 + sc_ * SHM_V, pa0, pa1, pa2, pa3);
;     ...
;     __builtin_amdgcn_s_setprio(0);
;     if (hi == 0) li_l[r32] = l_reg; asm volatile("s_waitcnt lgkmcnt(0)" ::: "memory");
;     float rli[16];
; #pragma unroll
;     for (int r = 0; r < 16; ++r) rli[r] = __builtin_amdgcn_rcpf(li_l[crow(r, hi)]);
;     if (mp == 0) {
; #pragma unroll
;       for (int d0 = 0; d0 < 4; ++d0)
; #pragma unroll
;         for (int r = 0; r < 16; r += 2) stash[(d0 * 8 + (r >> 1)) * 64] = cvt_pk_bf16(o[d0][r] * rli[r], o[d0][r + 1] * rli[r + 1]);
.LBB0_714:
	v_add_f32_e32 v64, 0, v128
	v_add_f32_e32 v65, 0, v129
	v_add_f32_e32 v68, v130, v64
	v_add_f32_e32 v69, v131, v65
	v_cvt_pk_bf16_f32 v64, v128, v129
	v_cvt_pk_bf16_f32 v65, v130, v131
	v_cvt_pk_bf16_f32 v66, v132, v133
	v_cvt_pk_bf16_f32 v67, v134, v135
	v_cvt_pk_bf16_f32 v70, v136, v137
	v_add_f32_e32 v68, v132, v68
	v_add_f32_e32 v69, v133, v69
	v_add_f32_e32 v68, v134, v68
	v_add_f32_e32 v69, v135, v69
	v_cvt_pk_bf16_f32 v71, v138, v139
	v_add_f32_e32 v68, v136, v68
	v_add_f32_e32 v69, v137, v69
	v_add_f32_e32 v68, v138, v68
	v_add_f32_e32 v69, v139, v69
	v_cvt_pk_bf16_f32 v72, v140, v141
	v_cvt_pk_bf16_f32 v73, v142, v143
	v_cvt_pk_bf16_f32 v74, v112, v113
	v_add_f32_e32 v68, v140, v68
	v_add_f32_e32 v69, v141, v69
	v_add_f32_e32 v68, v142, v68
	v_add_f32_e32 v69, v143, v69
	v_cvt_pk_bf16_f32 v75, v114, v115
	v_add_f32_e32 v68, v112, v68
	v_add_f32_e32 v69, v113, v69
	v_add_f32_e32 v68, v114, v68
	v_add_f32_e32 v69, v115, v69
	v_cvt_pk_bf16_f32 v76, v116, v117
	v_cvt_pk_bf16_f32 v77, v118, v119
	v_cvt_pk_bf16_f32 v78, v120, v121
	v_add_f32_e32 v68, v116, v68
	v_add_f32_e32 v69, v117, v69
	v_add_f32_e32 v68, v118, v68
	v_add_f32_e32 v69, v119, v69
	v_cvt_pk_bf16_f32 v79, v122, v123
	v_add_f32_e32 v68, v120, v68
	v_add_f32_e32 v69, v121, v69
	v_add_f32_e32 v68, v122, v68
	v_add_f32_e32 v69, v123, v69
	v_cvt_pk_bf16_f32 v80, v124, v125
	v_cvt_pk_bf16_f32 v81, v126, v127
	s_nop 0
	v_add_f32_e32 v68, v124, v68
	v_add_f32_e32 v69, v125, v69
	v_add_f32_e32 v68, v126, v68
	v_add_f32_e32 v69, v127, v69
	s_nop 0
	v_add_f32_e32 v68, v68, v69
	v_mov_b32_e32 v69, v68
	s_nop 1
	v_permlane32_swap_b32_e32 v68, v69
	s_cmp_lg_u32 0, -1
	s_cselect_b32 s24, 0, 0
	s_add_i32 s24, s24, 0x8000
	v_add_u32_e32 v86, s24, v179
	ds_read_b64_tr_b16 v[82:83], v86 offset:0
	ds_read_b64_tr_b16 v[84:85], v86 offset:0x800
	ds_read_b64_tr_b16 v[92:93], v86 offset:0x1000
	ds_read_b64_tr_b16 v[94:95], v86 offset:0x1800
	ds_read_b64_tr_b16 v[96:97], v86 offset:0x2000
	ds_read_b64_tr_b16 v[98:99], v86 offset:0x2800
	ds_read_b64_tr_b16 v[100:101], v86 offset:0x3000
	ds_read_b64_tr_b16 v[102:103], v86 offset:0x3800
	ds_read_b64_tr_b16 v[104:105], v86 offset:0x200
	ds_read_b64_tr_b16 v[106:107], v86 offset:0xa00
	ds_read_b64_tr_b16 v[108:109], v86 offset:0x1200
	ds_read_b64_tr_b16 v[110:111], v86 offset:0x1a00
	ds_read_b64_tr_b16 v[112:113], v86 offset:0x2200
	ds_read_b64_tr_b16 v[114:115], v86 offset:0x2a00
	ds_read_b64_tr_b16 v[116:117], v86 offset:0x3200
	ds_read_b64_tr_b16 v[118:119], v86 offset:0x3a00
	s_waitcnt lgkmcnt(8)
	s_nop 0
	v_mfma_f32_32x32x16_bf16 v[48:63], v[64:67], v[82:85], v[48:63]
	v_mfma_f32_32x32x16_bf16 v[48:63], v[70:73], v[92:95], v[48:63]
	v_mfma_f32_32x32x16_bf16 v[48:63], v[74:77], v[96:99], v[48:63]
	v_mfma_f32_32x32x16_bf16 v[48:63], v[78:81], v[100:103], v[48:63]
	ds_read_b64_tr_b16 v[82:83], v86 offset:0x400
	ds_read_b64_tr_b16 v[84:85], v86 offset:0xc00
	ds_read_b64_tr_b16 v[92:93], v86 offset:0x1400
	ds_read_b64_tr_b16 v[94:95], v86 offset:0x1c00
	ds_read_b64_tr_b16 v[96:97], v86 offset:0x2400
	ds_read_b64_tr_b16 v[98:99], v86 offset:0x2c00
	ds_read_b64_tr_b16 v[100:101], v86 offset:0x3400
	ds_read_b64_tr_b16 v[102:103], v86 offset:0x3c00
	s_waitcnt lgkmcnt(8)
	v_mfma_f32_32x32x16_bf16 v[32:47], v[64:67], v[104:107], v[32:47]
	v_mfma_f32_32x32x16_bf16 v[32:47], v[70:73], v[108:111], v[32:47]
	v_mfma_f32_32x32x16_bf16 v[32:47], v[74:77], v[112:115], v[32:47]
	v_mfma_f32_32x32x16_bf16 v[32:47], v[78:81], v[116:119], v[32:47]
	ds_read_b64_tr_b16 v[104:105], v86 offset:0x600
	ds_read_b64_tr_b16 v[106:107], v86 offset:0xe00
	ds_read_b64_tr_b16 v[108:109], v86 offset:0x1600
	ds_read_b64_tr_b16 v[110:111], v86 offset:0x1e00
	ds_read_b64_tr_b16 v[112:113], v86 offset:0x2600
	ds_read_b64_tr_b16 v[114:115], v86 offset:0x2e00
	ds_read_b64_tr_b16 v[116:117], v86 offset:0x3600
	ds_read_b64_tr_b16 v[118:119], v86 offset:0x3e00
	s_waitcnt lgkmcnt(8)
	v_mfma_f32_32x32x16_bf16 v[16:31], v[64:67], v[82:85], v[16:31]
	v_mfma_f32_32x32x16_bf16 v[16:31], v[70:73], v[92:95], v[16:31]
	v_mfma_f32_32x32x16_bf16 v[16:31], v[74:77], v[96:99], v[16:31]
	v_mfma_f32_32x32x16_bf16 v[16:31], v[78:81], v[100:103], v[16:31]
	s_waitcnt lgkmcnt(0)
	v_mfma_f32_32x32x16_bf16 v[0:15], v[64:67], v[104:107], v[0:15]
	v_mfma_f32_32x32x16_bf16 v[0:15], v[70:73], v[108:111], v[0:15]
	v_mfma_f32_32x32x16_bf16 v[0:15], v[74:77], v[112:115], v[0:15]
	v_mfma_f32_32x32x16_bf16 v[0:15], v[78:81], v[116:119], v[0:15]
	s_setprio 0
	s_and_saveexec_b64 s[68:69], s[0:1]
	v_add_f32_e32 v64, v88, v89
	v_fmac_f32_e32 v64, v178, v185
	v_add_f32_e32 v65, v68, v69
	v_fmac_f32_e32 v65, v64, v90
	ds_write_b32 v177, v65
	s_or_b64 exec, exec, s[68:69]
	s_waitcnt lgkmcnt(0)
	v_add_u32_e32 v80, s19, v168
	s_lshl_b32 s0, s18, 13
	ds_read_b128 v[64:67], v80
	s_add_i32 s0, s0, 0
	v_lshl_add_u32 v68, v169, 2, s0
	v_add_u32_e32 v81, 0x12800, v68
	ds_read_b128 v[68:71], v80 offset:32
	s_waitcnt lgkmcnt(1)
	v_rcp_f32_e32 v72, v64
	v_rcp_f32_e32 v73, v65
	v_rcp_f32_e32 v74, v66
	v_rcp_f32_e32 v75, v67
	ds_read_b128 v[64:67], v80 offset:64
	s_waitcnt lgkmcnt(1)
	v_rcp_f32_e32 v76, v68
	v_rcp_f32_e32 v77, v69
	v_rcp_f32_e32 v78, v70
	v_rcp_f32_e32 v79, v71
	ds_read_b128 v[68:71], v80 offset:96
	v_pk_mul_f32 v[48:49], v[48:49], v[72:73]
	s_waitcnt lgkmcnt(1)
	v_rcp_f32_e32 v64, v64
	v_cvt_pk_bf16_f32 v80, v48, v49
	v_pk_mul_f32 v[48:49], v[50:51], v[74:75]
	v_rcp_f32_e32 v65, v65
	v_cvt_pk_bf16_f32 v48, v48, v49
	v_rcp_f32_e32 v66, v66
	v_rcp_f32_e32 v67, v67
	ds_write2st64_b32 v81, v80, v48 offset1:1
	v_pk_mul_f32 v[48:49], v[52:53], v[76:77]
	s_waitcnt lgkmcnt(1)
;     ...
;   const size_t qrow0 = (size_t)b * SEQ + (size_t)qb * 256 + wid * QBLK;
;   const bf16_t* Vh = V + (size_t)b * NKV * LD + h * 128;
;   {
;     const bf16_t* Kh = K + (size_t)b * NKV * LD + h * 128 + mp * 64;
;     const bf16_t* Qw = Q + (qrow0 + r32) * LD + h * 128 + mp * 64 + hi * 8;
;     float l_reg = 0; f32x16 o[4] = {}; bf16x8 qr[4]; float nz_ = 0.f; asm volatile("" : "+v"(nz_)); f32x16 negm; _Pragma("unroll") for (int r = 0; r < 16; ++r) negm[r] = nz_; asm volatile("" : "+v"(negm));
; #pragma unroll
;     ...
;     for (int r = 0; r < 16; ++r) rli[r] = __builtin_amdgcn_rcpf(li_l[crow(r, hi)]);
;     if (mp == 0) {
; #pragma unroll
;       for (int d0 = 0; d0 < 4; ++d0)
; #pragma unroll
;         for (int r = 0; r < 16; r += 2) stash[(d0 * 8 + (r >> 1)) * 64] = cvt_pk_bf16(o[d0][r] * rli[r], o[d0][r + 1] * rli[r + 1]);
;     } else {
;       float ss[16];
; #pragma unroll
;       for (int r = 0; r < 16; ++r) ss[r] = 0.f;
; #pragma unroll
;       for (int d0 = 0; d0 < 4; ++d0)
; #pragma unroll
;         for (int r = 0; r < 16; r += 2) { const unsigned w = stash[(d0 * 8 + (r >> 1)) * 64];
;           const float a0 = bf_lo(w) - lam * (o[d0][r] * rli[r]), a1 = bf_hi(w) - lam * (o[d0][r + 1] * rli[r + 1]);
;           o[d0][r] = a0; o[d0][r + 1] = a1; ss[r] += a0 * a0; ss[r + 1] += a1 * a1; }
; #pragma unroll
;       for (int r = 0; r < 16; ++r) { float s = ss[r];
;         s += __shfl_xor(s, 1); s += __shfl_xor(s, 2); s += __shfl_xor(s, 4); s += __shfl_xor(s, 8); s += __shfl_xor(s, 16);
;         ss[r] = (1.0f - LAM_INIT) / sqrtf(s * (1.0f / 128.0f) + EPS); }
;       bf16_t* stg = (bf16_t*)(lds + OFF_ST) + wid * 4096;
; #pragma unroll
;       for (int d0 = 0; d0 < 4; ++d0) { const float g = subln_g[d0 * 32 + r32];
; #pragma unroll
;         for (int r = 0; r < 16; ++r) { const unsigned w = cvt_pk_bf16(o[d0][r] * ss[r] * g, 0.f);
;           stg[crow(r, hi) * 128 + d0 * 32 + r32] = (bf16_t)(w & 0xffffu); } }
;       asm volatile("s_waitcnt lgkmcnt(0)" ::: "memory");
;       const char* ob = (const char*)(O + qrow0 * LD + h * 128);
;       const unsigned lo = (unsigned)((lane >> 4) * LD + (lane & 15) * 8) * 2u;
; #pragma unroll
;       for (int i = 0; i < 8; ++i) { const u32x4 v = *(const u32x4*)(stg + (i * 4 + (lane >> 4)) * 128 + (lane & 15) * 8); *(u32x4*)((char*)ob + lo) = v; ob += 4 * LD * 2; }
;     }
;     __syncthreads();
	v_rcp_f32_e32 v68, v68
	v_cvt_pk_bf16_f32 v50, v48, v49
	v_pk_mul_f32 v[48:49], v[54:55], v[78:79]
	v_rcp_f32_e32 v69, v69
	v_cvt_pk_bf16_f32 v48, v48, v49
	v_rcp_f32_e32 v70, v70
	v_rcp_f32_e32 v71, v71
	ds_write2st64_b32 v81, v50, v48 offset0:2 offset1:3
	v_pk_mul_f32 v[48:49], v[56:57], v[64:65]
	v_pk_mul_f32 v[32:33], v[32:33], v[72:73]
	v_cvt_pk_bf16_f32 v50, v48, v49
	v_pk_mul_f32 v[48:49], v[58:59], v[66:67]
	v_pk_mul_f32 v[16:17], v[16:17], v[72:73]
	v_cvt_pk_bf16_f32 v48, v48, v49
	ds_write2st64_b32 v81, v50, v48 offset0:4 offset1:5
	v_pk_mul_f32 v[48:49], v[60:61], v[68:69]
	v_pk_mul_f32 v[0:1], v[0:1], v[72:73]
	v_cvt_pk_bf16_f32 v50, v48, v49
	v_pk_mul_f32 v[48:49], v[62:63], v[70:71]
	v_mov_b32_e32 v169, v167
	v_cvt_pk_bf16_f32 v48, v48, v49
	ds_write2st64_b32 v81, v50, v48 offset0:6 offset1:7
	v_cvt_pk_bf16_f32 v48, v32, v33
	v_pk_mul_f32 v[32:33], v[34:35], v[74:75]
	s_nop 0
	v_cvt_pk_bf16_f32 v32, v32, v33
	ds_write2st64_b32 v81, v48, v32 offset0:8 offset1:9
	v_pk_mul_f32 v[32:33], v[36:37], v[76:77]
	s_nop 0
	v_cvt_pk_bf16_f32 v34, v32, v33
	v_pk_mul_f32 v[32:33], v[38:39], v[78:79]
	s_nop 0
	v_cvt_pk_bf16_f32 v32, v32, v33
	ds_write2st64_b32 v81, v34, v32 offset0:10 offset1:11
	v_pk_mul_f32 v[32:33], v[40:41], v[64:65]
	s_nop 0
	v_cvt_pk_bf16_f32 v34, v32, v33
	v_pk_mul_f32 v[32:33], v[42:43], v[66:67]
	s_nop 0
	v_cvt_pk_bf16_f32 v32, v32, v33
	ds_write2st64_b32 v81, v34, v32 offset0:12 offset1:13
	v_pk_mul_f32 v[32:33], v[44:45], v[68:69]
	s_nop 0
	v_cvt_pk_bf16_f32 v34, v32, v33
	v_pk_mul_f32 v[32:33], v[46:47], v[70:71]
	s_nop 0
	v_cvt_pk_bf16_f32 v32, v32, v33
	ds_write2st64_b32 v81, v34, v32 offset0:14 offset1:15
	v_cvt_pk_bf16_f32 v32, v16, v17
	v_pk_mul_f32 v[16:17], v[18:19], v[74:75]
	s_nop 0
	v_cvt_pk_bf16_f32 v16, v16, v17
	ds_write2st64_b32 v81, v32, v16 offset0:16 offset1:17
	v_pk_mul_f32 v[16:17], v[20:21], v[76:77]
	s_nop 0
	v_cvt_pk_bf16_f32 v18, v16, v17
	v_pk_mul_f32 v[16:17], v[22:23], v[78:79]
	s_nop 0
	v_cvt_pk_bf16_f32 v16, v16, v17
	ds_write2st64_b32 v81, v18, v16 offset0:18 offset1:19
	v_pk_mul_f32 v[16:17], v[24:25], v[64:65]
	s_nop 0
	v_cvt_pk_bf16_f32 v18, v16, v17
	v_pk_mul_f32 v[16:17], v[26:27], v[66:67]
	s_nop 0
	v_cvt_pk_bf16_f32 v16, v16, v17
	ds_write2st64_b32 v81, v18, v16 offset0:20 offset1:21
	v_pk_mul_f32 v[16:17], v[28:29], v[68:69]
	s_nop 0
	v_cvt_pk_bf16_f32 v18, v16, v17
	v_pk_mul_f32 v[16:17], v[30:31], v[70:71]
	s_nop 0
	v_cvt_pk_bf16_f32 v16, v16, v17
	ds_write2st64_b32 v81, v18, v16 offset0:22 offset1:23
	v_cvt_pk_bf16_f32 v16, v0, v1
	v_pk_mul_f32 v[0:1], v[2:3], v[74:75]
	s_nop 0
	v_cvt_pk_bf16_f32 v0, v0, v1
	ds_write2st64_b32 v81, v16, v0 offset0:24 offset1:25
	v_pk_mul_f32 v[0:1], v[4:5], v[76:77]
	s_nop 0
	v_cvt_pk_bf16_f32 v2, v0, v1
	v_pk_mul_f32 v[0:1], v[6:7], v[78:79]
	s_nop 0
	v_cvt_pk_bf16_f32 v0, v0, v1
	ds_write2st64_b32 v81, v2, v0 offset0:26 offset1:27
	v_pk_mul_f32 v[0:1], v[8:9], v[64:65]
	v_mov_b32_e32 v64, v167
	v_cvt_pk_bf16_f32 v2, v0, v1
	v_pk_mul_f32 v[0:1], v[10:11], v[66:67]
	s_nop 0
	v_cvt_pk_bf16_f32 v0, v0, v1
	ds_write2st64_b32 v81, v2, v0 offset0:28 offset1:29
	v_pk_mul_f32 v[0:1], v[12:13], v[68:69]
	s_nop 0
	v_cvt_pk_bf16_f32 v2, v0, v1
	v_pk_mul_f32 v[0:1], v[14:15], v[70:71]
	s_nop 0
	v_cvt_pk_bf16_f32 v0, v0, v1
	v_mov_b32_e32 v1, v160
	ds_write2st64_b32 v81, v2, v0 offset0:30 offset1:31
	s_waitcnt lgkmcnt(0)
	s_barrier
	s_nop 0
	v_readfirstlane_b32 s0, v1
	s_ashr_i32 s18, s0, 6
	s_lshl_b32 s1, s18, 5
	s_ashr_i32 s19, s1, 31
	s_add_u32 s14, s14, s1
	v_and_b32_e32 v178, 31, v1
	s_addc_u32 s15, s15, s19
	v_or_b32_e32 v2, s14, v178
	v_mov_b32_e32 v3, s15
	v_lshlrev_b64 v[2:3], 11, v[2:3]
	v_bfe_u32 v0, v1, 5, 1
	v_lshl_add_u64 v[2:3], s[26:27], 0, v[2:3]
	v_lshl_add_u64 v[2:3], v[2:3], 0, s[6:7]
	v_lshlrev_b32_e32 v168, 4, v0
	v_lshl_add_u64 v[2:3], v[2:3], 0, v[168:169]
	v_mov_b32_e32 v65, v64
	v_mov_b32_e32 v66, v64
	v_mov_b32_e32 v67, v64
	v_mov_b32_e32 v68, v64
	v_mov_b32_e32 v69, v64
	v_mov_b32_e32 v70, v64
	v_mov_b32_e32 v71, v64
	v_mov_b32_e32 v72, v64
	v_mov_b32_e32 v73, v64
	v_mov_b32_e32 v74, v64
	v_mov_b32_e32 v75, v64
	v_mov_b32_e32 v76, v64
	v_mov_b32_e32 v77, v64
	v_mov_b32_e32 v78, v64
	v_mov_b32_e32 v79, v64
	global_load_dwordx4 v[156:159], v[2:3], off offset:128 nt
	global_load_dwordx4 v[152:155], v[2:3], off offset:160 nt
	global_load_dwordx4 v[148:151], v[2:3], off offset:192 nt
	global_load_dwordx4 v[144:147], v[2:3], off offset:224 nt
	s_cmp_lt_i32 s18, 4
	s_cbranch_scc1 .LBB0_718
	s_setprio 1
; #define WAIT_BAR() asm volatile("s_waitcnt vmcnt(0) lgkmcnt(0)\n\ts_barrier" ::: "memory")
;     ...
;   { const int kkl = (lane >> 2) & 7, cl = 32 * (lane >> 5) + (lane & 3) * 8;
;     const int kk0 = 8 * (wid >> 1) + kkl, kk1 = 8 * ((wid + 8) >> 1) + kkl;
;     const int key0 = (kk0 & ~0xC) | ((kk0 & 4) << 1) | ((kk0 & 8) >> 1), key1 = (kk1 & ~0xC) | ((kk1 & 4) << 1) | ((kk1 & 8) >> 1);
;     vo0 = (unsigned)(key0 * LD + 64 * (wid & 1) + cl) * 2u; vo1 = (unsigned)(key1 * LD + 64 * (wid & 1) + cl) * 2u; }
;     ...
;     DMA(0, 0); DMA(1, 1); WAIT_BAR();
;     { qkt(pA0, pA1, K_lds, qr, r32, hi); rowdecide(rowmax16(pA0), pA0, pA1, negm, alA);
.LBB0_718:
	s_ashr_i32 s1, s0, 4
	s_and_b32 s19, s1, 0x3ffff0
	v_and_b32_e32 v169, 63, v1
	v_bfe_u32 v3, v1, 2, 2
	v_and_b32_e32 v4, 32, v1
	v_lshlrev_b32_e32 v177, 3, v1
	s_add_i32 s34, s18, 8
	v_lshrrev_b32_e32 v1, 2, v1
	s_and_b32 s1, s1, 8
	s_lshl_b32 s24, s34, 2
	v_and_b32_e32 v1, 4, v1
	s_or_b32 s1, s19, s1
	s_lshl_b32 s19, s34, 2
	v_or3_b32 v5, s1, v3, v1
	s_and_b32 s1, s24, 0x3ffff0
	s_and_b32 s19, s19, 8
	s_or_b32 s1, s1, s19
	v_or3_b32 v1, s1, v3, v1
	v_lshlrev_b32_e32 v2, 11, v169
	v_and_or_b32 v4, v177, 24, v4
	v_lshlrev_b32_e32 v3, 10, v5
	s_and_b32 s1, s0, 64
	v_lshlrev_b32_e32 v1, 10, v1
	v_or3_b32 v3, v3, s1, v4
	v_or3_b32 v1, v1, s1, v4
	v_lshl_add_u32 v166, s18, 4, v2
	v_lshlrev_b32_e32 v170, 1, v1
	v_lshlrev_b32_e32 v1, 1, v3
	v_lshl_add_u64 v[2:3], s[64:65], 0, v[166:167]
	s_mov_b64 s[24:25], 0x80
	v_lshl_add_u64 v[32:33], v[2:3], 0, s[24:25]
	s_lshl_b32 s24, s18, 10
	s_cmp_lg_u32 0, -1
	s_cselect_b32 s1, 0, 0
	s_add_i32 s19, s24, s1
	s_add_i32 s25, s19, 0xc000
	s_mov_b32 s35, m0
	s_mov_b32 m0, s25
	s_nop 0
	global_load_lds_dwordx4 v[32:33], off
	s_mov_b32 m0, s35
	v_mov_b32_e32 v166, v1
	v_lshl_add_u64 v[4:5], s[52:53], 0, v[166:167]
	s_mov_b32 s25, m0
	s_mov_b32 m0, s19
	s_nop 0
	global_load_lds_dwordx4 v[4:5], off
	s_mov_b32 m0, s25
	v_mov_b32_e32 v171, v167
	s_lshl_b32 s25, s34, 10
	v_lshl_add_u64 v[4:5], s[52:53], 0, v[170:171]
	s_add_i32 s34, s25, s1
	s_mov_b32 s35, m0
	s_mov_b32 m0, s34
	s_nop 0
	global_load_lds_dwordx4 v[4:5], off
	s_mov_b32 m0, s35
	v_lshl_add_u64 v[2:3], v[2:3], 0, s[12:13]
	s_add_i32 s19, s19, 0xe000
	s_mov_b32 s34, m0
	s_mov_b32 m0, s19
	s_nop 0
	global_load_lds_dwordx4 v[2:3], off
	s_mov_b32 m0, s34
	s_addk_i32 s1, 0x4000
	v_lshl_add_u64 v[2:3], s[54:55], 0, v[166:167]
	s_add_i32 s19, s24, s1
	s_mov_b32 s34, m0
	s_mov_b32 m0, s19
	s_nop 0
	global_load_lds_dwordx4 v[2:3], off
	s_mov_b32 m0, s34
	v_lshl_add_u64 v[2:3], s[54:55], 0, v[170:171]
	s_add_i32 s1, s25, s1
	s_mov_b32 s19, m0
	s_mov_b32 m0, s1
	s_nop 0
	global_load_lds_dwordx4 v[2:3], off
	s_mov_b32 m0, s19
	v_lshlrev_b32_e32 v179, 10, v0
	v_lshlrev_b32_e32 v183, 4, v178
	s_waitcnt vmcnt(0) lgkmcnt(0)
	s_barrier
	v_add3_u32 v42, 0, v179, v183
	ds_read_b128 v[0:3], v42 offset:49152
	ds_read_b128 v[4:7], v42 offset:49664
	s_waitcnt vmcnt(3) lgkmcnt(1)
	v_mfma_f32_32x32x16_bf16 v[16:31], v[0:3], v[156:159], 0
	ds_read_b128 v[34:37], v42 offset:51200
	ds_read_b128 v[38:41], v42 offset:51712
	v_mov_b32_e32 v184, 1.0
	s_waitcnt lgkmcnt(2)
	v_mfma_f32_32x32x16_bf16 v[0:15], v[4:7], v[156:159], 0
	s_waitcnt vmcnt(2) lgkmcnt(0)
	v_mfma_f32_32x32x16_bf16 v[0:15], v[38:41], v[152:155], v[0:15]
	v_mfma_f32_32x32x16_bf16 v[16:31], v[34:37], v[152:155], v[16:31]
	ds_read_b128 v[34:37], v42 offset:53248
	ds_read_b128 v[38:41], v42 offset:53760
	s_waitcnt vmcnt(1) lgkmcnt(0)
	v_mfma_f32_32x32x16_bf16 v[0:15], v[38:41], v[148:151], v[0:15]
	v_mfma_f32_32x32x16_bf16 v[16:31], v[34:37], v[148:151], v[16:31]
	ds_read_b128 v[34:37], v42 offset:55296
	ds_read_b128 v[38:41], v42 offset:55808
	s_waitcnt vmcnt(0) lgkmcnt(0)
	v_mfma_f32_32x32x16_bf16 v[0:15], v[38:41], v[144:147], v[0:15]
	v_mfma_f32_32x32x16_bf16 v[16:31], v[34:37], v[144:147], v[16:31]
	s_nop 10
	v_max_f32_e32 v36, v1, v1
	v_max_f32_e32 v37, v0, v0
	v_max_f32_e32 v36, v37, v36
	v_max3_f32 v37, v3, v4, v5
	v_max3_f32 v36, v36, v2, v6
	v_max3_f32 v37, v37, v8, v9
	v_max3_f32 v36, v36, v7, v10
	v_max3_f32 v34, v16, v17, v18
	v_max3_f32 v35, v19, v20, v21
	v_max3_f32 v34, v34, v22, v23
	v_max3_f32 v35, v35, v24, v25
	v_max3_f32 v34, v34, v26, v27
	v_max3_f32 v37, v37, v12, v13
	v_max3_f32 v36, v36, v11, v14
	v_max3_f32 v35, v35, v28, v29
	v_max3_f32 v34, v34, v30, v31
	v_max3_f32 v36, v36, v15, v37
	v_max3_f32 v34, v34, v35, v36
	v_mov_b32_e32 v35, v34
	s_nop 1
	v_permlane32_swap_b32_e32 v34, v35
	v_max_f32_e32 v35, v35, v35
	v_max_f32_e32 v34, v34, v34
	v_max_f32_e32 v34, v34, v35
	v_cmp_lt_f32_e32 vcc, s47, v34
	s_cbranch_vccnz .LBB0_743

;     ...
;     f32x16 pA0, pA1, pB0, pB1; float alA, alB; bf16x8 pa0, pa1, pa2, pa3;
;     int sp = 0, sc_ = 1, sn = 2;
.LBB0_720:
	s_lshl_b32 s43, s34, 13
	s_mov_b32 s42, s38
	v_lshl_add_u32 v187, s42, 13, v186
	ds_read_b128 v[112:115], v187 offset:49152
	ds_read_b128 v[188:191], v187 offset:49664
	ds_read_b128 v[192:195], v187 offset:51200
	ds_read_b128 v[196:199], v187 offset:51712
	s_add_i32 s38, s43, s39
	s_mov_b32 m0, s38
	v_lshl_add_u64 v[212:213], s[4:5], 0, v[166:167]
	global_load_lds_dwordx4 v[172:173], off
	s_lshl_b32 s38, s34, 14
	s_add_i32 s45, s38, s24
	s_mov_b32 m0, s45
	v_lshl_add_u64 v[214:215], s[4:5], 0, v[170:171]
	global_load_lds_dwordx4 v[212:213], off
	s_add_i32 s38, s38, s25
	s_mov_b32 m0, s38
	s_mov_b32 s38, s44
	global_load_lds_dwordx4 v[214:215], off
	s_waitcnt lgkmcnt(3)
	v_mfma_f32_32x32x16_bf16 v[128:143], v[112:115], v[156:159], v[64:79]
	ds_read_b128 v[224:227], v187 offset:53248
	ds_read_b128 v[200:203], v187 offset:53760
	v_add_f32_e32 v116, v98, v96
	v_add_f32_e32 v117, v99, v97
	v_cvt_pk_bf16_f32 v96, v96, v97
	v_cvt_pk_bf16_f32 v97, v98, v99
	v_cvt_pk_bf16_f32 v98, v100, v101
	v_cvt_pk_bf16_f32 v99, v102, v103
	v_add_f32_e32 v100, v100, v116
	v_add_f32_e32 v101, v101, v117
	s_waitcnt lgkmcnt(4)
	v_mfma_f32_32x32x16_bf16 v[112:127], v[188:191], v[156:159], v[64:79]
	v_add_f32_e32 v100, v102, v100
	v_add_f32_e32 v101, v103, v101
	s_waitcnt lgkmcnt(3)
	v_mfma_f32_32x32x16_bf16 v[128:143], v[192:195], v[152:155], v[128:143]
	ds_read_b128 v[228:231], v187 offset:55296
	ds_read_b128 v[232:235], v187 offset:55808
	v_add_f32_e32 v100, v104, v100
	v_add_f32_e32 v101, v105, v101
	v_add_f32_e32 v204, v106, v100
	v_add_f32_e32 v205, v107, v101
	v_cvt_pk_bf16_f32 v100, v104, v105
	v_cvt_pk_bf16_f32 v101, v106, v107
	v_cvt_pk_bf16_f32 v102, v108, v109
	v_cvt_pk_bf16_f32 v103, v110, v111
	s_waitcnt lgkmcnt(4)
	v_mfma_f32_32x32x16_bf16 v[112:127], v[196:199], v[152:155], v[112:127]
	v_add_f32_e32 v104, v108, v204
	v_add_f32_e32 v105, v109, v205
	v_add_f32_e32 v192, v110, v104
	v_add_f32_e32 v193, v111, v105
	s_waitcnt lgkmcnt(3)
	v_mfma_f32_32x32x16_bf16 v[128:143], v[224:227], v[148:151], v[128:143]
	v_add_f32_e32 v187, v80, v192
	v_add_f32_e32 v192, v81, v193
	v_add_f32_e32 v187, v82, v187
	v_add_f32_e32 v192, v83, v192
	v_cvt_pk_bf16_f32 v80, v80, v81
	v_cvt_pk_bf16_f32 v81, v82, v83
	v_cvt_pk_bf16_f32 v82, v84, v85
	v_cvt_pk_bf16_f32 v83, v86, v87
	s_waitcnt lgkmcnt(2)
	v_mfma_f32_32x32x16_bf16 v[112:127], v[200:203], v[148:151], v[112:127]
	s_lshl_b32 s44, s38, 14
	v_add_u32_e32 v191, s44, v185
	ds_read_b64_tr_b16 v[196:197], v191 offset:0
	ds_read_b64_tr_b16 v[198:199], v191 offset:0x800
	ds_read_b64_tr_b16 v[200:201], v191 offset:0x1000
	ds_read_b64_tr_b16 v[202:203], v191 offset:0x1800
	ds_read_b64_tr_b16 v[212:213], v191 offset:0x2000
	ds_read_b64_tr_b16 v[214:215], v191 offset:0x2800
	v_add_f32_e32 v84, v84, v187
	v_add_f32_e32 v85, v85, v192
	v_add_f32_e32 v84, v86, v84
	v_add_f32_e32 v85, v87, v85
	s_waitcnt lgkmcnt(7)
	v_mfma_f32_32x32x16_bf16 v[128:143], v[228:231], v[144:147], v[128:143]
	ds_read_b64_tr_b16 v[192:193], v191 offset:0x3000
	ds_read_b64_tr_b16 v[194:195], v191 offset:0x3800
	ds_read_b64_tr_b16 v[216:217], v191 offset:0x200
	ds_read_b64_tr_b16 v[218:219], v191 offset:0xa00
	v_add_f32_e32 v84, v88, v84
	v_add_f32_e32 v85, v89, v85
	v_add_f32_e32 v187, v90, v84
	v_add_f32_e32 v188, v91, v85
	v_cvt_pk_bf16_f32 v84, v88, v89
	v_cvt_pk_bf16_f32 v85, v90, v91
	v_cvt_pk_bf16_f32 v86, v92, v93
	v_cvt_pk_bf16_f32 v87, v94, v95
	s_waitcnt lgkmcnt(10)
	v_mfma_f32_32x32x16_bf16 v[112:127], v[232:235], v[144:147], v[112:127]
	v_add_f32_e32 v88, v92, v187
	v_add_f32_e32 v89, v93, v188
	v_add_f32_e32 v88, v94, v88
	v_add_f32_e32 v89, v95, v89
	ds_read_b64_tr_b16 v[220:221], v191 offset:0x1200
	ds_read_b64_tr_b16 v[222:223], v191 offset:0x1a00
	ds_read_b64_tr_b16 v[224:225], v191 offset:0x2200
	ds_read_b64_tr_b16 v[226:227], v191 offset:0x2a00
	s_waitcnt lgkmcnt(12)
	v_mfma_f32_32x32x16_bf16 v[48:63], v[96:99], v[196:199], v[48:63]
	v_max_f32_e32 v90, v128, v129
	v_max3_f32 v91, v131, v132, v133
	v_max3_f32 v90, v90, v130, v134
	v_max3_f32 v91, v91, v136, v137
	ds_read_b64_tr_b16 v[196:197], v191 offset:0x3200
	ds_read_b64_tr_b16 v[198:199], v191 offset:0x3a00
	s_waitcnt lgkmcnt(12)
	v_mfma_f32_32x32x16_bf16 v[48:63], v[100:103], v[200:203], v[48:63]
	v_max3_f32 v90, v90, v135, v138
	v_max3_f32 v91, v91, v140, v141
	v_max3_f32 v90, v90, v139, v142
	v_max3_f32 v90, v90, v143, v91
	v_add_f32_e32 v188, v88, v89
	v_mov_b32_e32 v189, v188
	ds_read_b64_tr_b16 v[200:201], v191 offset:0x400
	ds_read_b64_tr_b16 v[202:203], v191 offset:0xc00
	s_waitcnt lgkmcnt(12)
	v_mfma_f32_32x32x16_bf16 v[48:63], v[80:83], v[212:215], v[48:63]
	v_max3_f32 v88, v112, v113, v114
	v_max3_f32 v89, v115, v116, v117
	v_max3_f32 v88, v88, v118, v119
	v_max3_f32 v89, v89, v120, v121
	v_permlane32_swap_b32_e32 v188, v189
	v_max3_f32 v88, v88, v122, v123
	ds_read_b64_tr_b16 v[212:213], v191 offset:0x1400
	ds_read_b64_tr_b16 v[214:215], v191 offset:0x1c00
	s_waitcnt lgkmcnt(12)
	v_mfma_f32_32x32x16_bf16 v[48:63], v[84:87], v[192:195], v[48:63]
	v_max3_f32 v89, v89, v124, v125
	v_max3_f32 v88, v88, v126, v127
	v_max3_f32 v88, v90, v88, v89
	v_mov_b32_e32 v89, v88
	ds_read_b64_tr_b16 v[192:193], v191 offset:0x2400
	ds_read_b64_tr_b16 v[194:195], v191 offset:0x2c00
	s_waitcnt lgkmcnt(12)
	v_mfma_f32_32x32x16_bf16 v[32:47], v[96:99], v[216:219], v[32:47]
	v_permlane32_swap_b32_e32 v88, v89
	v_max_f32_e32 v88, v88, v89
	v_cmp_lt_f32_e32 vcc, s47, v88
	v_mov_b32_e32 v190, 1.0
	s_cbranch_vccnz .LBB0_732

;     ...
;     f32x16 pA0, pA1, pB0, pB1; float alA, alB; bf16x8 pa0, pa1, pa2, pa3;
;     int sp = 0, sc_ = 1, sn = 2;
.LBB0_725:
	s_add_u32 s48, s4, 0x20000
	s_addc_u32 s49, s5, 0
	s_lshl_b32 s45, s38, 13
	s_add_i32 s45, s45, s39
	s_waitcnt vmcnt(0) lgkmcnt(0)
	s_barrier
	v_add_u32_e32 v187, s43, v186
	ds_read_b128 v[80:83], v187 offset:49152
	ds_read_b128 v[192:195], v187 offset:49664
	ds_read_b128 v[196:199], v187 offset:51200
	ds_read_b128 v[200:203], v187 offset:51712
	s_mov_b32 m0, s45
	v_lshl_add_u64 v[212:213], v[172:173], 0, s[8:9]
	global_load_lds_dwordx4 v[212:213], off
	s_add_i32 s45, s44, s24
	s_mov_b32 m0, s45
	v_lshl_add_u64 v[214:215], s[48:49], 0, v[166:167]
	global_load_lds_dwordx4 v[214:215], off
	s_add_i32 s44, s44, s25
	s_mov_b32 m0, s44
	v_lshl_add_u64 v[212:213], s[48:49], 0, v[170:171]
	global_load_lds_dwordx4 v[212:213], off
	s_waitcnt lgkmcnt(3)
	v_mfma_f32_32x32x16_bf16 v[96:111], v[80:83], v[156:159], v[64:79]
	ds_read_b128 v[224:227], v187 offset:53248
	ds_read_b128 v[204:207], v187 offset:53760
	v_add_f32_e32 v84, v130, v128
	v_add_f32_e32 v85, v131, v129
	v_cvt_pk_bf16_f32 v128, v128, v129
	v_cvt_pk_bf16_f32 v129, v130, v131
	v_cvt_pk_bf16_f32 v130, v132, v133
	v_cvt_pk_bf16_f32 v131, v134, v135
	v_add_f32_e32 v80, v132, v84
	v_add_f32_e32 v81, v133, v85
	v_add_f32_e32 v132, v134, v80
	v_add_f32_e32 v133, v135, v81
	s_waitcnt lgkmcnt(4)
	v_mfma_f32_32x32x16_bf16 v[80:95], v[192:195], v[156:159], v[64:79]
	s_waitcnt lgkmcnt(3)
	v_mfma_f32_32x32x16_bf16 v[96:111], v[196:199], v[152:155], v[96:111]
	ds_read_b128 v[228:231], v187 offset:55296
	ds_read_b128 v[232:235], v187 offset:55808
	v_add_f32_e32 v132, v136, v132
	v_add_f32_e32 v133, v137, v133
	v_add_f32_e32 v191, v138, v132
	v_add_f32_e32 v208, v139, v133
	v_cvt_pk_bf16_f32 v132, v136, v137
	v_cvt_pk_bf16_f32 v133, v138, v139
	v_cvt_pk_bf16_f32 v134, v140, v141
	v_cvt_pk_bf16_f32 v135, v142, v143
	s_waitcnt lgkmcnt(4)
	v_mfma_f32_32x32x16_bf16 v[80:95], v[200:203], v[152:155], v[80:95]
	v_add_f32_e32 v136, v140, v191
	v_add_f32_e32 v137, v141, v208
	v_add_f32_e32 v191, v142, v136
	v_add_f32_e32 v196, v143, v137
	s_waitcnt lgkmcnt(3)
	v_mfma_f32_32x32x16_bf16 v[96:111], v[224:227], v[148:151], v[96:111]
	v_add_f32_e32 v187, v112, v191
	v_add_f32_e32 v191, v113, v196
	v_add_f32_e32 v187, v114, v187
	v_add_f32_e32 v191, v115, v191
	v_cvt_pk_bf16_f32 v112, v112, v113
	v_cvt_pk_bf16_f32 v113, v114, v115
	v_cvt_pk_bf16_f32 v114, v116, v117
	v_cvt_pk_bf16_f32 v115, v118, v119
	s_waitcnt lgkmcnt(2)
	v_mfma_f32_32x32x16_bf16 v[80:95], v[204:207], v[148:151], v[80:95]
	v_lshl_add_u32 v208, s42, 14, v185
	ds_read_b64_tr_b16 v[200:201], v208 offset:0
	ds_read_b64_tr_b16 v[202:203], v208 offset:0x800
	ds_read_b64_tr_b16 v[192:193], v208 offset:0x1000
	ds_read_b64_tr_b16 v[194:195], v208 offset:0x1800
	ds_read_b64_tr_b16 v[204:205], v208 offset:0x2000
	ds_read_b64_tr_b16 v[206:207], v208 offset:0x2800
	v_add_f32_e32 v116, v116, v187
	v_add_f32_e32 v117, v117, v191
	v_add_f32_e32 v116, v118, v116
	v_add_f32_e32 v117, v119, v117
	s_waitcnt lgkmcnt(7)
	v_mfma_f32_32x32x16_bf16 v[96:111], v[228:231], v[144:147], v[96:111]
	ds_read_b64_tr_b16 v[212:213], v208 offset:0x3000
	ds_read_b64_tr_b16 v[214:215], v208 offset:0x3800
	ds_read_b64_tr_b16 v[216:217], v208 offset:0x200
	ds_read_b64_tr_b16 v[218:219], v208 offset:0xa00
	v_add_f32_e32 v116, v120, v116
	v_add_f32_e32 v117, v121, v117
	v_add_f32_e32 v187, v122, v116
	v_add_f32_e32 v191, v123, v117
	v_cvt_pk_bf16_f32 v116, v120, v121
	v_cvt_pk_bf16_f32 v117, v122, v123
	v_cvt_pk_bf16_f32 v118, v124, v125
	v_cvt_pk_bf16_f32 v119, v126, v127
	s_waitcnt lgkmcnt(10)
	v_mfma_f32_32x32x16_bf16 v[80:95], v[232:235], v[144:147], v[80:95]
	v_add_f32_e32 v120, v124, v187
	v_add_f32_e32 v121, v125, v191
	v_add_f32_e32 v120, v126, v120
	v_add_f32_e32 v121, v127, v121
	ds_read_b64_tr_b16 v[220:221], v208 offset:0x1200
	ds_read_b64_tr_b16 v[222:223], v208 offset:0x1a00
	ds_read_b64_tr_b16 v[224:225], v208 offset:0x2200
	ds_read_b64_tr_b16 v[226:227], v208 offset:0x2a00
	s_waitcnt lgkmcnt(12)
	v_mfma_f32_32x32x16_bf16 v[48:63], v[128:131], v[200:203], v[48:63]
	v_max_f32_e32 v122, v96, v97
	v_max3_f32 v123, v99, v100, v101
	v_max3_f32 v122, v122, v98, v102
	v_max3_f32 v123, v123, v104, v105
	ds_read_b64_tr_b16 v[200:201], v208 offset:0x3200
	ds_read_b64_tr_b16 v[202:203], v208 offset:0x3a00
	s_waitcnt lgkmcnt(12)
	v_mfma_f32_32x32x16_bf16 v[48:63], v[132:135], v[192:195], v[48:63]
	v_max3_f32 v122, v122, v103, v106
	v_max3_f32 v123, v123, v108, v109
	v_max3_f32 v122, v122, v107, v110
	v_max3_f32 v122, v122, v111, v123
	v_add_f32_e32 v120, v120, v121
	v_mov_b32_e32 v121, v120
	ds_read_b64_tr_b16 v[192:193], v208 offset:0x400
	ds_read_b64_tr_b16 v[194:195], v208 offset:0xc00
	s_waitcnt lgkmcnt(12)
	v_mfma_f32_32x32x16_bf16 v[48:63], v[112:115], v[204:207], v[48:63]
	v_max3_f32 v123, v80, v81, v82
	v_max3_f32 v124, v83, v84, v85
	v_max3_f32 v123, v123, v86, v87
	v_max3_f32 v124, v124, v88, v89
	v_permlane32_swap_b32_e32 v120, v121
	v_max3_f32 v123, v123, v90, v91
	ds_read_b64_tr_b16 v[204:205], v208 offset:0x1400
	ds_read_b64_tr_b16 v[206:207], v208 offset:0x1c00
	s_waitcnt lgkmcnt(12)
	v_mfma_f32_32x32x16_bf16 v[48:63], v[116:119], v[212:215], v[48:63]
	v_max3_f32 v124, v124, v92, v93
	v_max3_f32 v123, v123, v94, v95
	v_max3_f32 v122, v122, v123, v124
	v_mov_b32_e32 v123, v122
	ds_read_b64_tr_b16 v[212:213], v208 offset:0x2400
	ds_read_b64_tr_b16 v[214:215], v208 offset:0x2c00
	s_waitcnt lgkmcnt(12)
	v_mfma_f32_32x32x16_bf16 v[32:47], v[128:131], v[216:219], v[32:47]
	v_permlane32_swap_b32_e32 v122, v123
	v_max_f32_e32 v122, v122, v123
	v_cmp_lt_f32_e32 vcc, s47, v122
	v_mov_b32_e32 v187, 1.0
	s_cbranch_vccnz .LBB0_733

.LBB0_734:
	v_add3_u32 v166, s72, v183, v179
	ds_read_b128 v[112:115], v166
	ds_read_b128 v[170:173], v166 offset:512
	s_waitcnt lgkmcnt(1)
	v_mfma_f32_32x32x16_bf16 v[128:143], v[112:115], v[156:159], v[64:79]
	ds_read_b128 v[188:191], v166 offset:2048
	ds_read_b128 v[192:195], v166 offset:2560
	v_add_f32_e32 v116, 0, v96
	v_add_f32_e32 v117, 0, v97
	v_add_f32_e32 v116, v98, v116
	v_add_f32_e32 v117, v99, v117
	v_cvt_pk_bf16_f32 v96, v96, v97
	v_cvt_pk_bf16_f32 v97, v98, v99
	v_cvt_pk_bf16_f32 v98, v100, v101
	v_cvt_pk_bf16_f32 v99, v102, v103
	s_nop 0
	v_add_f32_e32 v100, v100, v116
	v_add_f32_e32 v101, v101, v117
	s_waitcnt lgkmcnt(2)
	v_mfma_f32_32x32x16_bf16 v[112:127], v[170:173], v[156:159], v[64:79]
	v_add_f32_e32 v100, v102, v100
	v_add_f32_e32 v101, v103, v101
	s_waitcnt lgkmcnt(1)
	v_mfma_f32_32x32x16_bf16 v[128:143], v[188:191], v[152:155], v[128:143]
	ds_read_b128 v[156:159], v166 offset:4096
	ds_read_b128 v[170:173], v166 offset:4608
	v_add_f32_e32 v100, v104, v100
	v_add_f32_e32 v101, v105, v101
	v_add_f32_e32 v183, v106, v100
	v_add_f32_e32 v184, v107, v101
	v_cvt_pk_bf16_f32 v100, v104, v105
	v_cvt_pk_bf16_f32 v101, v106, v107
	v_cvt_pk_bf16_f32 v102, v108, v109
	v_cvt_pk_bf16_f32 v103, v110, v111
	s_waitcnt lgkmcnt(2)
	v_mfma_f32_32x32x16_bf16 v[112:127], v[192:195], v[152:155], v[112:127]
	v_add_f32_e32 v104, v108, v183
	v_add_f32_e32 v105, v109, v184
	v_add_f32_e32 v183, v110, v104
	v_add_f32_e32 v184, v111, v105
	s_waitcnt lgkmcnt(1)
	v_mfma_f32_32x32x16_bf16 v[128:143], v[156:159], v[148:151], v[128:143]
	ds_read_b128 v[104:107], v166 offset:6144
	ds_read_b128 v[108:111], v166 offset:6656
	v_add_f32_e32 v152, v80, v183
	v_add_f32_e32 v153, v81, v184
	v_add_f32_e32 v152, v82, v152
	v_add_f32_e32 v153, v83, v153
	v_cvt_pk_bf16_f32 v80, v80, v81
	v_cvt_pk_bf16_f32 v81, v82, v83
	v_cvt_pk_bf16_f32 v82, v84, v85
	v_cvt_pk_bf16_f32 v83, v86, v87
	s_waitcnt lgkmcnt(2)
	v_mfma_f32_32x32x16_bf16 v[112:127], v[170:173], v[148:151], v[112:127]
	v_add_f32_e32 v84, v84, v152
	v_add_f32_e32 v85, v85, v153
	v_add_f32_e32 v84, v86, v84
	v_add_f32_e32 v85, v87, v85
	s_waitcnt lgkmcnt(1)
	v_mfma_f32_32x32x16_bf16 v[128:143], v[104:107], v[144:147], v[128:143]
	v_add_f32_e32 v84, v88, v84
	v_add_f32_e32 v85, v89, v85
	v_add_f32_e32 v148, v90, v84
	v_add_f32_e32 v149, v91, v85
	v_cvt_pk_bf16_f32 v84, v88, v89
	v_cvt_pk_bf16_f32 v85, v90, v91
	v_cvt_pk_bf16_f32 v86, v92, v93
	v_cvt_pk_bf16_f32 v87, v94, v95
	s_waitcnt lgkmcnt(0)
	v_mfma_f32_32x32x16_bf16 v[112:127], v[108:111], v[144:147], v[112:127]
	s_nop 1
	v_max_f32_e32 v90, v129, v129
	v_max_f32_e32 v91, v128, v128
	v_max_f32_e32 v90, v91, v90
	v_max3_f32 v91, v131, v132, v133
	v_max3_f32 v90, v90, v130, v134
	v_max3_f32 v91, v91, v136, v137
	v_max3_f32 v90, v90, v135, v138
	v_add_f32_e32 v88, v92, v148
	v_add_f32_e32 v89, v93, v149
	v_max3_f32 v91, v91, v140, v141
	v_max3_f32 v90, v90, v139, v142
	v_add_f32_e32 v88, v94, v88
	v_add_f32_e32 v89, v95, v89
	v_max3_f32 v90, v90, v143, v91
	s_nop 0
	v_add_f32_e32 v88, v88, v89
	v_mov_b32_e32 v89, v88
	s_nop 1
	v_permlane32_swap_b32_e32 v88, v89
	v_max3_f32 v91, v112, v113, v114
	v_max3_f32 v92, v115, v116, v117
	v_max3_f32 v91, v91, v118, v119
	v_max3_f32 v92, v92, v120, v121
	v_max3_f32 v91, v91, v122, v123
	v_max3_f32 v92, v92, v124, v125
	v_max3_f32 v91, v91, v126, v127
	v_max3_f32 v90, v90, v91, v92
	v_mov_b32_e32 v91, v90
	s_nop 1
	v_permlane32_swap_b32_e32 v90, v91
	v_max_f32_e32 v91, v91, v91
	v_max_f32_e32 v90, v90, v90
	v_max_f32_e32 v91, v90, v91
	v_cmp_lt_f32_e32 vcc, s47, v91
	v_mov_b32_e32 v90, 1.0
	s_cbranch_vccnz .LBB0_744

; #define SBAR() __builtin_amdgcn_sched_barrier(0)
; #define FINA(I, P0, P1) finA<I>(P0, P1, ps0, ps1, cv_, pa0, pa1, pa2, pa3)
;     ...
;     { float ps0 = 0.f, ps1 = 0.f; unsigned cv_[4];
;       FINA(0, pB0, pB1); FINA(1, pB0, pB1); FINA(2, pB0, pB1); FINA(3, pB0, pB1); FINA(4, pB0, pB1); FINA(5, pB0, pB1); FINA(6, pB0, pB1); FINA(7, pB0, pB1);
;       float ps = ps0 + ps1; auto rr = __builtin_amdgcn_permlane32_swap(__float_as_uint(ps), __float_as_uint(ps), false, false);
;       ps = __uint_as_float(rr[0]) + __uint_as_float(rr[1]); l_reg = l_reg * alB + ps; }
;     SBAR();
;     pv_d0(o, vb0 + sc_ * SHM_V, pa0, pa1, pa2, pa3);
;     ...
;     __builtin_amdgcn_s_setprio(0);
;     if (hi == 0) li_l[r32] = l_reg; asm volatile("s_waitcnt lgkmcnt(0)" ::: "memory");
.LBB0_739:
	v_add_f32_e32 v64, 0, v128
	v_add_f32_e32 v65, 0, v129
	v_add_f32_e32 v68, v130, v64
	v_add_f32_e32 v69, v131, v65
	v_cvt_pk_bf16_f32 v64, v128, v129
	v_cvt_pk_bf16_f32 v65, v130, v131
	v_cvt_pk_bf16_f32 v66, v132, v133
	v_cvt_pk_bf16_f32 v67, v134, v135
	v_cvt_pk_bf16_f32 v70, v136, v137
	v_add_f32_e32 v68, v132, v68
	v_add_f32_e32 v69, v133, v69
	v_add_f32_e32 v68, v134, v68
	v_add_f32_e32 v69, v135, v69
	v_cvt_pk_bf16_f32 v71, v138, v139
	v_add_f32_e32 v68, v136, v68
	v_add_f32_e32 v69, v137, v69
	v_add_f32_e32 v68, v138, v68
	v_add_f32_e32 v69, v139, v69
	v_cvt_pk_bf16_f32 v72, v140, v141
	v_cvt_pk_bf16_f32 v73, v142, v143
	v_cvt_pk_bf16_f32 v74, v112, v113
	v_add_f32_e32 v68, v140, v68
	v_add_f32_e32 v69, v141, v69
	v_add_f32_e32 v68, v142, v68
	v_add_f32_e32 v69, v143, v69
	v_cvt_pk_bf16_f32 v75, v114, v115
	v_add_f32_e32 v68, v112, v68
	v_add_f32_e32 v69, v113, v69
	v_add_f32_e32 v68, v114, v68
	v_add_f32_e32 v69, v115, v69
	v_cvt_pk_bf16_f32 v76, v116, v117
	v_cvt_pk_bf16_f32 v77, v118, v119
	v_cvt_pk_bf16_f32 v78, v120, v121
	v_add_f32_e32 v68, v116, v68
	v_add_f32_e32 v69, v117, v69
	v_add_f32_e32 v68, v118, v68
	v_add_f32_e32 v69, v119, v69
	v_cvt_pk_bf16_f32 v79, v122, v123
	v_add_f32_e32 v68, v120, v68
	v_add_f32_e32 v69, v121, v69
	v_add_f32_e32 v68, v122, v68
	v_add_f32_e32 v69, v123, v69
	v_cvt_pk_bf16_f32 v80, v124, v125
	v_cvt_pk_bf16_f32 v81, v126, v127
	s_nop 0
	v_add_f32_e32 v68, v124, v68
	v_add_f32_e32 v69, v125, v69
	v_add_f32_e32 v68, v126, v68
	v_add_f32_e32 v69, v127, v69
	s_nop 0
	v_add_f32_e32 v68, v68, v69
	v_mov_b32_e32 v69, v68
	s_nop 1
	v_permlane32_swap_b32_e32 v68, v69
	s_cmp_lg_u32 0, -1
	s_cselect_b32 s4, 0, 0
	s_add_i32 s4, s4, 0x8000
	v_add_u32_e32 v86, s4, v182
	ds_read_b64_tr_b16 v[82:83], v86 offset:0
	ds_read_b64_tr_b16 v[84:85], v86 offset:0x800
	ds_read_b64_tr_b16 v[92:93], v86 offset:0x1000
	ds_read_b64_tr_b16 v[94:95], v86 offset:0x1800
	ds_read_b64_tr_b16 v[96:97], v86 offset:0x2000
	ds_read_b64_tr_b16 v[98:99], v86 offset:0x2800
	ds_read_b64_tr_b16 v[100:101], v86 offset:0x3000
	ds_read_b64_tr_b16 v[102:103], v86 offset:0x3800
	ds_read_b64_tr_b16 v[104:105], v86 offset:0x200
	ds_read_b64_tr_b16 v[106:107], v86 offset:0xa00
	ds_read_b64_tr_b16 v[108:109], v86 offset:0x1200
	ds_read_b64_tr_b16 v[110:111], v86 offset:0x1a00
	ds_read_b64_tr_b16 v[112:113], v86 offset:0x2200
	ds_read_b64_tr_b16 v[114:115], v86 offset:0x2a00
	ds_read_b64_tr_b16 v[116:117], v86 offset:0x3200
	ds_read_b64_tr_b16 v[118:119], v86 offset:0x3a00
	s_waitcnt lgkmcnt(8)
	s_nop 0
	v_mfma_f32_32x32x16_bf16 v[48:63], v[64:67], v[82:85], v[48:63]
	v_mfma_f32_32x32x16_bf16 v[48:63], v[70:73], v[92:95], v[48:63]
	v_mfma_f32_32x32x16_bf16 v[48:63], v[74:77], v[96:99], v[48:63]
	v_mfma_f32_32x32x16_bf16 v[48:63], v[78:81], v[100:103], v[48:63]
	ds_read_b64_tr_b16 v[82:83], v86 offset:0x400
	ds_read_b64_tr_b16 v[84:85], v86 offset:0xc00
	ds_read_b64_tr_b16 v[92:93], v86 offset:0x1400
	ds_read_b64_tr_b16 v[94:95], v86 offset:0x1c00
	ds_read_b64_tr_b16 v[96:97], v86 offset:0x2400
	ds_read_b64_tr_b16 v[98:99], v86 offset:0x2c00
	ds_read_b64_tr_b16 v[100:101], v86 offset:0x3400
	ds_read_b64_tr_b16 v[102:103], v86 offset:0x3c00
	s_waitcnt lgkmcnt(8)
	v_mfma_f32_32x32x16_bf16 v[32:47], v[64:67], v[104:107], v[32:47]
	v_mfma_f32_32x32x16_bf16 v[32:47], v[70:73], v[108:111], v[32:47]
	v_mfma_f32_32x32x16_bf16 v[32:47], v[74:77], v[112:115], v[32:47]
	v_mfma_f32_32x32x16_bf16 v[32:47], v[78:81], v[116:119], v[32:47]
	ds_read_b64_tr_b16 v[104:105], v86 offset:0x600
	ds_read_b64_tr_b16 v[106:107], v86 offset:0xe00
	ds_read_b64_tr_b16 v[108:109], v86 offset:0x1600
	ds_read_b64_tr_b16 v[110:111], v86 offset:0x1e00
	ds_read_b64_tr_b16 v[112:113], v86 offset:0x2600
	ds_read_b64_tr_b16 v[114:115], v86 offset:0x2e00
	ds_read_b64_tr_b16 v[116:117], v86 offset:0x3600
	ds_read_b64_tr_b16 v[118:119], v86 offset:0x3e00
	s_waitcnt lgkmcnt(8)
	v_mfma_f32_32x32x16_bf16 v[16:31], v[64:67], v[82:85], v[16:31]
	v_mfma_f32_32x32x16_bf16 v[16:31], v[70:73], v[92:95], v[16:31]
	v_mfma_f32_32x32x16_bf16 v[16:31], v[74:77], v[96:99], v[16:31]
	v_mfma_f32_32x32x16_bf16 v[16:31], v[78:81], v[100:103], v[16:31]
	s_waitcnt lgkmcnt(0)
	v_mfma_f32_32x32x16_bf16 v[0:15], v[64:67], v[104:107], v[0:15]
	v_mfma_f32_32x32x16_bf16 v[0:15], v[70:73], v[108:111], v[0:15]
	v_mfma_f32_32x32x16_bf16 v[0:15], v[74:77], v[112:115], v[0:15]
	v_mfma_f32_32x32x16_bf16 v[0:15], v[78:81], v[116:119], v[0:15]
	s_setprio 0
	s_and_saveexec_b64 s[4:5], s[0:1]
	s_cbranch_execz .LBB0_690
	v_add_f32_e32 v64, v88, v89
	v_fmac_f32_e32 v64, v181, v187
	v_add_f32_e32 v65, v68, v69
	v_fmac_f32_e32 v65, v64, v90
	ds_write_b32 v180, v65
	s_branch .LBB0_690
